# speedup vs baseline: 1.0155x; 1.0043x over previous
; __device__ __forceinline__ float bf2f(u16 h) { return __uint_as_float(((unsigned)h) << 16); }
; __device__ __forceinline__ u16 f2bf(float f) { return (u16)(cvtpk(f, 0.f) & 0xffffu); }
; template <int DK, bool KBIAS, int ROPE>
; __device__ __forceinline__ void attn_pp(const AttnArgs& a) {
;     ...
;   bf16x8 qr[ND];
; #pragma unroll
;   for (int d0 = 0; d0 < ND; ++d0) qr[d0] = *(const bf16x8*)(a.Q + (size_t)qpos * a.ldq + d0 * 16 + hi * 8);
;   if constexpr (ROPE == 1) {
; #pragma unroll
;     for (int dd = 0; dd < 2; ++dd)
; #pragma unroll
;       for (int e = 0; e < 8; ++e) {
;         float c, s; rope_cs(qpos, dd * 16 + hi * 8 + e, 64, c, s);
;         const float x1 = bf2f((u16)qr[8 + dd][e]), x2 = bf2f((u16)qr[10 + dd][e]);
;         qr[8 + dd][e] = (short)f2bf(x1 * c - x2 * s); qr[10 + dd][e] = (short)f2bf(x2 * c + x1 * s);
;       }
;   }
;   if constexpr (ROPE == 2) {
; #pragma unroll
;     for (int e = 0; e < 8; ++e) {
;       float c, s; rope_cs(qpos, hi * 8 + e, 32, c, s);
;       const float x1 = bf2f((u16)qr[0][e]), x2 = bf2f((u16)qr[1][e]);
;       qr[0][e] = (short)f2bf(x1 * c - x2 * s); qr[1][e] = (short)f2bf(x2 * c + x1 * s);
;     }
; __global__ void __launch_bounds__(NTHREADS) fwd_megakernel(Params p) {
;     ...
;         const int g16 = xq * 2 + (n >> 6), r = n & 63, b = g16 >> 3, h = g16 & 7, c = (r >> 1) & 1, vh = r & 1;
;         a.qb = 15 - (r >> 2);
;         const size_t t0 = (size_t)b * SEQ;
;         a.Q = proj + t0 * NEP + E_DQ + (h * 2 + c) * 128; a.ldq = NEP;
;         a.K1 = proj + t0 * NEP + E_DK + (h * 2 + c) * 128; a.ldk1 = NEP;
;         a.K2 = nullptr; a.ldk2 = 0;
;         a.V = proj + t0 * NEP + E_DV + h * 256 + vh * 128; a.ldv = NEP;
;         a.O = ob + t0 * 4096 + (h * 2 + c) * 256 + vh * 128; a.ldo = 4096;
.LBB0_1132:
	s_or_b64 exec, exec, s[4:5]
	s_add_i32 s34, s56, 0x80
	s_add_i32 s56, s56, 0xffffffc0
	s_cmp_lt_i32 s56, 0
	s_cselect_b32 s56, s34, s56
	s_cmpk_lt_i32 s56, 0x80
	s_cbranch_scc0 .Lp4_perm_mla
	s_and_b32 s34, s56, 4
	s_lshl_b32 s34, s34, 4
	s_lshr_b32 s35, s56, 3
	s_lshl_b32 s35, s35, 2
	s_and_b32 s56, s56, 3
	s_or_b32 s56, s56, s34
	s_or_b32 s56, s56, s35
	s_branch .Lp4_perm_done
.Lp4_perm_mla:
	s_and_b32 s34, s56, 3
	s_lshl_b32 s34, s34, 4
	s_sub_i32 s35, s56, 0x80
	s_lshr_b32 s35, s35, 2
	s_or_b32 s56, s34, s35
	s_or_b32 s56, s56, 0x80
.Lp4_perm_done:
	s_cmpk_lt_i32 s56, 0x80
	s_cbranch_scc0 .LBB0_1149
	s_ashr_i32 s4, s56, 6
	s_add_i32 s4, s4, s74
	s_ashr_i32 s50, s4, 3
	s_and_b32 s4, s4, 7
	s_bfe_u32 s80, s56, 0x10001
	s_ashr_i32 s51, s50, 31
	s_mul_i32 s52, s50, 0x5e00000
	s_mul_hi_i32 s53, s50, 0x5e00000
	s_add_u32 s5, s42, s52
	s_addc_u32 s34, s43, s53
	s_lshl_b32 s35, s4, 1
	s_or_b32 s57, s35, s80
	s_lshl_b32 s35, s57, 8
	s_add_u32 s35, s5, s35
	s_addc_u32 s38, s34, 0
	s_add_u32 s82, s35, 0x1c80
	s_addc_u32 s83, s38, 0
	s_add_u32 s54, s35, 0x2c80
	s_addc_u32 s55, s38, 0
	s_lshl_b32 s4, s4, 9
	s_add_u32 s4, s5, s4
	s_addc_u32 s5, s34, 0
	s_lshl_b32 s34, s56, 7
	s_and_b32 s34, s34, 0x80
	s_lshl_b32 s75, s34, 1
	s_add_u32 s4, s4, s75
	s_addc_u32 s5, s5, 0
	s_add_u32 s4, s4, 0x3c80
	v_mov_b32_e32 v171, v194
	s_addc_u32 s5, s5, 0
	s_not_b32 s34, s56
	v_readfirstlane_b32 s76, v171
	s_ashr_i32 s77, s76, 1
	s_lshl_b32 s34, s34, 6
	s_andn2_b32 s77, s77, 31
	s_and_b32 s78, s34, 0xf00
	v_and_b32_e32 v170, 31, v171
	s_add_i32 s38, s77, s78
	v_bfe_u32 v8, v171, 5, 1
	v_or_b32_e32 v172, s38, v170
	v_mov_b64_e32 v[0:1], s[82:83]
	v_mad_i64_i32 v[0:1], s[82:83], v172, s61, v[0:1]
	v_lshlrev_b32_e32 v180, 4, v8
	v_lshl_add_u64 v[10:11], v[0:1], 0, v[180:181]
	global_load_dwordx4 v[0:3], v[10:11], off
	global_load_dwordx4 v[4:7], v[10:11], off offset:32
	global_load_dwordx4 v[96:99], v[10:11], off offset:64
	global_load_dwordx4 v[100:103], v[10:11], off offset:96
	global_load_dwordx4 v[104:107], v[10:11], off offset:128
	global_load_dwordx4 v[108:111], v[10:11], off offset:160
	global_load_dwordx4 v[112:115], v[10:11], off offset:192
	global_load_dwordx4 v[116:119], v[10:11], off offset:224
	v_cvt_f32_ubyte0_e32 v9, v180
	v_mul_f32_e32 v9, 0xbd000000, v9
	v_mul_f32_e32 v9, 0x419773da, v9
	v_cvt_f32_i32_e32 v11, v172
	v_exp_f32_e32 v9, v9
	s_ashr_i32 s79, s76, 8
	s_lshl_b32 s83, s79, 5
	v_mov_b64_e32 v[50:51], s[54:55]
	v_mul_f32_e32 v9, v9, v11
	v_mul_f32_e32 v10, 0.15915494, v9
	v_floor_f32_e32 v10, v10
	v_fma_f32 v9, v9, 0.15915494, -v10
	v_cos_f32_e32 v12, v9
	v_sin_f32_e32 v13, v9
	v_mov_b32_e32 v161, v181
	v_mov_b64_e32 v[52:53], s[4:5]
	s_cmp_lg_u32 s79, 1
	s_waitcnt vmcnt(7)
	v_lshlrev_b32_e32 v14, 16, v0
	s_waitcnt vmcnt(6)
	v_lshlrev_b32_e32 v15, 16, v4
	v_pk_mul_f32 v[16:17], v[12:13], v[14:15]
	s_nop 0
	v_sub_f32_e32 v9, v16, v17
	v_mov_b32_e32 v16, v13
	v_mov_b32_e32 v17, v12
	v_pk_mul_f32 v[12:13], v[16:17], v[14:15]
	v_cvt_pk_bf16_f32 v10, v9, v181
	v_and_b32_e32 v15, 0xffff0000, v4
	v_add_f32_e32 v9, v12, v13
	v_or_b32_e32 v12, 2, v180
	v_cvt_f32_ubyte0_e32 v12, v12
	v_mul_f32_e32 v12, 0xbd000000, v12
	v_mul_f32_e32 v12, 0x419773da, v12
	v_exp_f32_e32 v12, v12
	v_and_b32_e32 v14, 0xffff0000, v0
	v_cvt_pk_bf16_f32 v9, v9, v181
	v_mul_f32_e32 v12, v12, v11
	v_mul_f32_e32 v13, 0.15915494, v12
	v_floor_f32_e32 v13, v13
	v_fma_f32 v13, v12, 0.15915494, -v13
	v_cos_f32_e32 v12, v13
	v_sin_f32_e32 v13, v13
	s_nop 0
	v_pk_mul_f32 v[16:17], v[12:13], v[14:15]
	s_nop 0
	v_sub_f32_e32 v0, v16, v17
	v_mov_b32_e32 v16, v13
	v_mov_b32_e32 v17, v12
	v_pk_mul_f32 v[12:13], v[16:17], v[14:15]
	v_cvt_pk_bf16_f32 v4, v0, v181
	v_lshlrev_b32_e32 v17, 16, v5
	v_add_f32_e32 v0, v12, v13
	v_or_b32_e32 v12, 4, v180
	v_cvt_f32_ubyte0_e32 v12, v12
	v_mul_f32_e32 v12, 0xbd000000, v12
	v_mul_f32_e32 v12, 0x419773da, v12
	v_exp_f32_e32 v12, v12
	v_lshlrev_b32_e32 v16, 16, v1
	v_cvt_pk_bf16_f32 v0, v0, v181
	v_mul_f32_e32 v12, v12, v11
	v_mul_f32_e32 v13, 0.15915494, v12
	v_floor_f32_e32 v13, v13
	v_fma_f32 v12, v12, 0.15915494, -v13
	v_cos_f32_e32 v14, v12
	v_sin_f32_e32 v15, v12
	v_mov_b32_e32 v19, v14
	v_pk_mul_f32 v[12:13], v[14:15], v[16:17]
	v_mov_b32_e32 v18, v15
	v_sub_f32_e32 v12, v12, v13
	v_pk_mul_f32 v[14:15], v[18:19], v[16:17]
	v_cvt_pk_bf16_f32 v13, v12, v181
	v_and_b32_e32 v17, 0xffff0000, v5
	v_add_f32_e32 v12, v14, v15
	v_or_b32_e32 v14, 6, v180
	v_cvt_f32_ubyte0_e32 v14, v14
	v_mul_f32_e32 v14, 0xbd000000, v14
	v_mul_f32_e32 v14, 0x419773da, v14
	v_exp_f32_e32 v14, v14
	v_and_b32_e32 v16, 0xffff0000, v1
	v_cvt_pk_bf16_f32 v12, v12, v181
	v_mul_f32_e32 v14, v14, v11
	v_mul_f32_e32 v15, 0.15915494, v14
	v_floor_f32_e32 v15, v15
	v_fma_f32 v15, v14, 0.15915494, -v15
	v_cos_f32_e32 v14, v15
	v_sin_f32_e32 v15, v15
	s_nop 0
	v_pk_mul_f32 v[18:19], v[14:15], v[16:17]
	s_nop 0
	v_sub_f32_e32 v1, v18, v19
	v_mov_b32_e32 v18, v15
	v_mov_b32_e32 v19, v14
	v_pk_mul_f32 v[14:15], v[18:19], v[16:17]
	v_cvt_pk_bf16_f32 v5, v1, v181
	v_lshlrev_b32_e32 v19, 16, v6
	v_add_f32_e32 v1, v14, v15
	v_or_b32_e32 v14, 8, v180
	v_cvt_f32_ubyte0_e32 v14, v14
	v_mul_f32_e32 v14, 0xbd000000, v14
	v_mul_f32_e32 v14, 0x419773da, v14
	v_exp_f32_e32 v14, v14
	v_lshlrev_b32_e32 v18, 16, v2
	v_cvt_pk_bf16_f32 v1, v1, v181
	v_mul_f32_e32 v14, v14, v11
	v_mul_f32_e32 v15, 0.15915494, v14
	v_floor_f32_e32 v15, v15
	v_fma_f32 v14, v14, 0.15915494, -v15
; __device__ __forceinline__ float bf2f(u16 h) { return __uint_as_float(((unsigned)h) << 16); }
; __device__ __forceinline__ u16 f2bf(float f) { return (u16)(cvtpk(f, 0.f) & 0xffffu); }
; __device__ __forceinline__ int v_st(int k, int c) { const int kk = (k & ~0xC) | ((k & 4) << 1) | ((k & 8) >> 1); return ((kk >> 3) * 4 + (c >> 5)) * 512 + ((kk & 7) * 32 + (c & 31)) * 2; }
; template <int DK, bool KBIAS, int ROPE>
; __device__ __forceinline__ void attn_pp(const AttnArgs& a) {
;     ...
;   if constexpr (ROPE == 2) {
; #pragma unroll
;     for (int e = 0; e < 8; ++e) {
;       float c, s; rope_cs(qpos, hi * 8 + e, 32, c, s);
;       const float x1 = bf2f((u16)qr[0][e]), x2 = bf2f((u16)qr[1][e]);
;       qr[0][e] = (short)f2bf(x1 * c - x2 * s); qr[1][e] = (short)f2bf(x2 * c + x1 * s);
;     }
;   }
;   const int gt = tid & 255;
;   const int sr = grp * 32 + (gt >> 4), sc = (gt & 15) * 8;
;   const int sr2 = grp * 32 + (gt >> 3), sc2 = (gt & 7) * 8;
;   const int vst0 = v_st(sr, sc);
;   bf16x8 sk0, sk1, sk2, sv0, sv1; float sb = 0.f;
;   bf16x8 tk0, tk1, tk2, tv0, tv1; float tb = 0.f;
;     ...
;   __syncthreads();
;   LOADT(0); LOADT_B(1); WRITET(0, 0); LOADT(2); WRITET_B(1, 1);
;   __syncthreads();
;   if (grp == 1) __syncthreads();
	v_cos_f32_e32 v16, v14
	v_sin_f32_e32 v17, v14
	v_mov_b32_e32 v21, v16
	v_pk_mul_f32 v[14:15], v[16:17], v[18:19]
	v_mov_b32_e32 v20, v17
	v_sub_f32_e32 v14, v14, v15
	v_pk_mul_f32 v[16:17], v[20:21], v[18:19]
	v_cvt_pk_bf16_f32 v15, v14, v181
	v_and_b32_e32 v19, 0xffff0000, v6
	v_add_f32_e32 v14, v16, v17
	v_or_b32_e32 v16, 10, v180
	v_cvt_f32_ubyte0_e32 v16, v16
	v_mul_f32_e32 v16, 0xbd000000, v16
	v_mul_f32_e32 v16, 0x419773da, v16
	v_exp_f32_e32 v16, v16
	v_and_b32_e32 v18, 0xffff0000, v2
	v_cvt_pk_bf16_f32 v14, v14, v181
	v_mul_f32_e32 v16, v16, v11
	v_mul_f32_e32 v17, 0.15915494, v16
	v_floor_f32_e32 v17, v17
	v_fma_f32 v17, v16, 0.15915494, -v17
	v_cos_f32_e32 v16, v17
	v_sin_f32_e32 v17, v17
	s_nop 0
	v_pk_mul_f32 v[20:21], v[16:17], v[18:19]
	s_nop 0
	v_sub_f32_e32 v2, v20, v21
	v_mov_b32_e32 v20, v17
	v_mov_b32_e32 v21, v16
	v_pk_mul_f32 v[16:17], v[20:21], v[18:19]
	v_cvt_pk_bf16_f32 v6, v2, v181
	v_lshlrev_b32_e32 v21, 16, v7
	v_add_f32_e32 v2, v16, v17
	v_or_b32_e32 v16, 12, v180
	v_cvt_f32_ubyte0_e32 v16, v16
	v_mul_f32_e32 v16, 0xbd000000, v16
	v_mul_f32_e32 v16, 0x419773da, v16
	v_exp_f32_e32 v16, v16
	v_lshlrev_b32_e32 v20, 16, v3
	v_cvt_pk_bf16_f32 v2, v2, v181
	v_mul_f32_e32 v16, v16, v11
	v_mul_f32_e32 v17, 0.15915494, v16
	v_floor_f32_e32 v17, v17
	v_fma_f32 v16, v16, 0.15915494, -v17
	v_cos_f32_e32 v18, v16
	v_sin_f32_e32 v19, v16
	v_mov_b32_e32 v23, v18
	v_pk_mul_f32 v[16:17], v[18:19], v[20:21]
	v_mov_b32_e32 v22, v19
	v_sub_f32_e32 v16, v16, v17
	v_pk_mul_f32 v[18:19], v[22:23], v[20:21]
	v_cvt_pk_bf16_f32 v17, v16, v181
	v_and_b32_e32 v21, 0xffff0000, v7
	v_add_f32_e32 v16, v18, v19
	v_or_b32_e32 v18, 14, v180
	v_cvt_f32_ubyte0_e32 v18, v18
	v_mul_f32_e32 v18, 0xbd000000, v18
	v_mul_f32_e32 v18, 0x419773da, v18
	v_exp_f32_e32 v18, v18
	v_and_b32_e32 v20, 0xffff0000, v3
	v_cvt_pk_bf16_f32 v16, v16, v181
	v_mul_f32_e32 v11, v18, v11
	v_mul_f32_e32 v18, 0.15915494, v11
	v_floor_f32_e32 v18, v18
	v_fma_f32 v11, v11, 0.15915494, -v18
	v_cos_f32_e32 v18, v11
	v_sin_f32_e32 v19, v11
	s_nop 0
	v_pk_mul_f32 v[22:23], v[18:19], v[20:21]
	s_nop 0
	v_sub_f32_e32 v3, v22, v23
	v_mov_b32_e32 v22, v19
	v_mov_b32_e32 v23, v18
	v_pk_mul_f32 v[18:19], v[22:23], v[20:21]
	v_lshrrev_b32_e32 v20, 3, v171
	v_cvt_pk_bf16_f32 v11, v3, v181
	v_add_f32_e32 v3, v18, v19
	v_lshlrev_b32_e32 v18, 3, v171
	v_and_or_b32 v20, v20, 8, s83
	v_and_b32_e32 v19, 0x78, v18
	v_lshrrev_b32_e32 v20, 1, v20
	v_bfe_u32 v18, v18, 5, 2
	v_lshrrev_b32_e32 v21, 5, v171
	v_or_b32_e32 v18, v20, v18
	v_bfe_u32 v20, v171, 4, 2
	v_lshlrev_b32_e32 v160, 1, v19
	v_cvt_pk_bf16_f32 v7, v3, v181
	v_bfe_u32 v3, v171, 4, 4
	v_and_or_b32 v20, v21, 4, v20
	v_and_b32_e32 v19, 48, v160
	v_or_b32_e32 v54, s83, v3
	v_lshl_or_b32 v19, v20, 6, v19
	v_lshl_or_b32 v55, v18, 9, v19
	v_mad_i64_i32 v[18:19], s[54:55], v54, s61, v[50:51]
	v_or_b32_e32 v30, 16, v54
	v_lshl_add_u64 v[18:19], v[18:19], 0, v[160:161]
	v_mad_i64_i32 v[22:23], s[54:55], v30, s61, v[50:51]
	s_barrier
	global_load_dwordx4 v[18:21], v[18:19], off
	v_lshl_add_u64 v[22:23], v[22:23], 0, v[160:161]
	v_mad_i64_i32 v[26:27], s[4:5], v54, s61, v[52:53]
	global_load_dwordx4 v[22:25], v[22:23], off
	v_lshl_add_u64 v[26:27], v[26:27], 0, v[160:161]
	v_mad_i64_i32 v[30:31], s[4:5], v30, s61, v[52:53]
	global_load_dwordx4 v[26:29], v[26:27], off
	v_lshl_add_u64 v[30:31], v[30:31], 0, v[160:161]
	global_load_dwordx4 v[30:33], v[30:31], off
	v_add_u32_e32 v42, 64, v54
	v_add_u32_e32 v46, 0x50, v54
	v_mad_i64_i32 v[34:35], s[4:5], v42, s61, v[50:51]
	v_mad_i64_i32 v[38:39], s[4:5], v46, s61, v[50:51]
	v_mad_i64_i32 v[42:43], s[4:5], v42, s61, v[52:53]
	v_mad_i64_i32 v[46:47], s[4:5], v46, s61, v[52:53]
	s_movk_i32 s4, 0x110
	s_nop 0
	v_mul_lo_u32 v174, v54, s4
	v_lshl_add_u64 v[34:35], v[34:35], 0, v[160:161]
	v_lshl_add_u64 v[38:39], v[38:39], 0, v[160:161]
	v_lshl_add_u64 v[42:43], v[42:43], 0, v[160:161]
	v_lshl_add_u64 v[46:47], v[46:47], 0, v[160:161]
	v_add3_u32 v56, 16, v174, v160
	global_load_dwordx4 v[34:37], v[34:35], off
	v_add_u32_e32 v175, 16, v55
	global_load_dwordx4 v[38:41], v[38:39], off
	s_nop 0
	global_load_dwordx4 v[42:45], v[42:43], off
	s_nop 0
	global_load_dwordx4 v[46:49], v[46:47], off
	s_waitcnt vmcnt(7)
	ds_write_b128 v56, v[18:21]
	s_waitcnt vmcnt(6)
	ds_write_b128 v56, v[22:25] offset:4352
	v_add_u32_e32 v20, 0x80, v54
	v_mad_i64_i32 v[18:19], s[4:5], v20, s61, v[50:51]
	s_waitcnt vmcnt(5)
	ds_write_b128 v175, v[26:29] offset:52224
	s_waitcnt vmcnt(4)
	ds_write_b128 v175, v[30:33] offset:56320
	v_lshl_add_u64 v[18:19], v[18:19], 0, v[160:161]
	v_add_u32_e32 v21, 0x90, v54
	global_load_dwordx4 v[120:123], v[18:19], off
	v_mad_i64_i32 v[18:19], s[4:5], v21, s61, v[50:51]
	v_lshl_add_u64 v[18:19], v[18:19], 0, v[160:161]
	global_load_dwordx4 v[124:127], v[18:19], off
	v_mad_i64_i32 v[18:19], s[4:5], v20, s61, v[52:53]
	v_lshl_add_u64 v[18:19], v[18:19], 0, v[160:161]
	global_load_dwordx4 v[128:131], v[18:19], off
	v_mad_i64_i32 v[18:19], s[4:5], v21, s61, v[52:53]
	v_lshl_add_u64 v[18:19], v[18:19], 0, v[160:161]
	global_load_dwordx4 v[132:135], v[18:19], off
	v_add_u32_e32 v18, 0x10c00, v175
	s_waitcnt vmcnt(7)
	ds_write_b128 v56, v[34:37] offset:17408
	s_waitcnt vmcnt(6)
	ds_write_b128 v56, v[38:41] offset:21760
	s_waitcnt vmcnt(5)
	ds_write_b128 v18, v[42:45]
	s_waitcnt vmcnt(4)
	ds_write_b128 v18, v[46:49] offset:4096
	s_waitcnt lgkmcnt(0)
	s_barrier
	s_cbranch_scc1 .LBB0_1135
	s_barrier
